# grid barrier: non-leader workgroups poll the cross-XCD generation directly; L1 invalidate issued while waiting instead of after release
# speedup vs baseline: 1.0112x; 1.0063x over previous
.LBB0_86:
	v_readlane_b32 s4, v243, 5
	s_lshl_b32 s4, s4, 8
	v_readlane_b32 s6, v243, 3
	v_readlane_b32 s7, v243, 4
	s_add_u32 s4, s6, s4
	s_addc_u32 s5, s7, 0
	v_mov_b32_e32 v1, 0x1000
	v_mov_b32_e32 v3, 1
	global_atomic_add v3, v1, v3, s[4:5] offset:1024 sc0
	v_cvt_f32_u32_e32 v1, v2
	v_sub_u32_e32 v4, 0, v2
	v_rcp_iflag_f32_e32 v1, v1
	s_nop 0
	v_mul_f32_e32 v1, 0x4f7ffffe, v1
	v_cvt_u32_f32_e32 v1, v1
	v_mul_lo_u32 v4, v4, v1
	v_mul_hi_u32 v4, v1, v4
	v_add_u32_e32 v1, v1, v4
	s_waitcnt vmcnt(0)
	v_mul_hi_u32 v1, v3, v1
	v_mul_lo_u32 v4, v1, v2
	v_sub_u32_e32 v4, v3, v4
	v_add_u32_e32 v5, 1, v1
	v_cmp_ge_u32_e32 vcc, v4, v2
	v_add_u32_e32 v3, 1, v3
	s_nop 0
	v_cndmask_b32_e32 v1, v1, v5, vcc
	v_sub_u32_e32 v5, v4, v2
	v_cndmask_b32_e32 v4, v4, v5, vcc
	v_add_u32_e32 v5, 1, v1
	v_cmp_ge_u32_e32 vcc, v4, v2
	s_nop 1
	v_cndmask_b32_e32 v1, v1, v5, vcc
	v_mul_lo_u32 v4, v2, v1
	v_add_u32_e32 v2, v4, v2
	v_cmp_ne_u32_e32 vcc, v3, v2
	s_and_saveexec_b64 s[6:7], vcc
	s_xor_b64 s[6:7], exec, s[6:7]
	s_cbranch_execz .LBB0_100
	s_waitcnt lgkmcnt(0)
	buffer_inv sc1
	s_waitcnt vmcnt(0)
	v_mov_b32_e32 v0, 0xc3000
	global_load_dword v0, v0, s[92:93] offset:1280 sc1
	s_add_u32 s12, s92, 0xc3500
	s_addc_u32 s13, s93, 0
	s_waitcnt vmcnt(0)
	v_cmp_eq_u32_e32 vcc, v0, v1
	s_and_saveexec_b64 s[8:9], vcc
	s_cbranch_execz .LBB0_99
	s_add_u32 s10, s92, 0xc0200
	s_addc_u32 s11, s93, 0
	s_mov_b32 s26, 1
	s_mov_b64 s[16:17], 0
	v_mov_b32_e32 v0, 0
	s_branch .LBB0_90

.LBB0_99:
	s_or_b64 exec, exec, s[8:9]
	s_waitcnt vmcnt(0)
	s_waitcnt vmcnt(0)
.LBB0_100:
	s_andn2_saveexec_b64 s[6:7], s[6:7]
	s_cbranch_execz .LBB0_118
	s_mov_b64 s[6:7], exec
	buffer_wbl2 sc1
	buffer_inv sc1
	s_waitcnt lgkmcnt(0)
	s_waitcnt vmcnt(0)
	v_mbcnt_lo_u32_b32 v1, s6, 0
	v_mbcnt_hi_u32_b32 v1, s7, v1
	v_cmp_eq_u32_e32 vcc, 0, v1
	s_and_saveexec_b64 s[8:9], vcc
	s_cbranch_execz .LBB0_103
	s_bcnt1_i32_b64 s6, s[6:7]
	v_mov_b32_e32 v2, 0xc3000
	v_mov_b32_e32 v3, s6
	global_atomic_add v2, v2, v3, s[92:93] offset:1024 sc0

.LBB0_117:
	s_or_b64 exec, exec, s[6:7]
	v_mov_b32_e32 v0, 0x2000
	v_mov_b32_e32 v1, 1
	s_waitcnt vmcnt(0)
	global_atomic_add v0, v1, s[4:5] offset:1024
	s_waitcnt vmcnt(0)

.LBB0_391:
	v_readlane_b32 s4, v243, 5
	s_lshl_b32 s4, s4, 8
	v_readlane_b32 s6, v243, 3
	v_readlane_b32 s7, v243, 4
	s_add_u32 s4, s6, s4
	s_addc_u32 s5, s7, 0
	v_mov_b32_e32 v1, 0x1000
	v_mov_b32_e32 v3, 1
	global_atomic_add v3, v1, v3, s[4:5] offset:1024 sc0
	v_cvt_f32_u32_e32 v1, v2
	v_sub_u32_e32 v4, 0, v2
	v_rcp_iflag_f32_e32 v1, v1
	s_nop 0
	v_mul_f32_e32 v1, 0x4f7ffffe, v1
	v_cvt_u32_f32_e32 v1, v1
	v_mul_lo_u32 v4, v4, v1
	v_mul_hi_u32 v4, v1, v4
	v_add_u32_e32 v1, v1, v4
	s_waitcnt vmcnt(0)
	v_mul_hi_u32 v1, v3, v1
	v_mul_lo_u32 v4, v1, v2
	v_sub_u32_e32 v4, v3, v4
	v_add_u32_e32 v5, 1, v1
	v_cmp_ge_u32_e32 vcc, v4, v2
	v_add_u32_e32 v3, 1, v3
	s_nop 0
	v_cndmask_b32_e32 v1, v1, v5, vcc
	v_sub_u32_e32 v5, v4, v2
	v_cndmask_b32_e32 v4, v4, v5, vcc
	v_add_u32_e32 v5, 1, v1
	v_cmp_ge_u32_e32 vcc, v4, v2
	s_nop 1
	v_cndmask_b32_e32 v1, v1, v5, vcc
	v_mul_lo_u32 v4, v2, v1
	v_add_u32_e32 v2, v4, v2
	v_cmp_ne_u32_e32 vcc, v3, v2
	s_and_saveexec_b64 s[6:7], vcc
	s_xor_b64 s[6:7], exec, s[6:7]
	s_cbranch_execz .LBB0_405
	s_waitcnt lgkmcnt(0)
	buffer_inv sc1
	s_waitcnt vmcnt(0)
	v_mov_b32_e32 v0, 0xc3000
	global_load_dword v0, v0, s[92:93] offset:1280 sc1
	s_add_u32 s14, s92, 0xc3500
	s_addc_u32 s15, s93, 0
	s_waitcnt vmcnt(0)
	v_cmp_eq_u32_e32 vcc, v0, v1
	s_and_saveexec_b64 s[8:9], vcc
	s_cbranch_execz .LBB0_404
	s_add_u32 s10, s92, 0xc0200
	s_addc_u32 s11, s93, 0
	s_mov_b32 s26, 1
	s_mov_b64 s[16:17], 0
	v_mov_b32_e32 v0, 0
	s_branch .LBB0_395

.LBB0_606:
	v_readlane_b32 s2, v243, 5
	s_lshl_b32 s2, s2, 8
	v_readlane_b32 s4, v243, 3
	v_readlane_b32 s5, v243, 4
	s_add_u32 s2, s4, s2
	s_addc_u32 s3, s5, 0
	v_mov_b32_e32 v1, 0x1000
	v_mov_b32_e32 v3, 1
	global_atomic_add v3, v1, v3, s[2:3] offset:1024 sc0
	v_cvt_f32_u32_e32 v1, v2
	v_sub_u32_e32 v4, 0, v2
	v_rcp_iflag_f32_e32 v1, v1
	s_nop 0
	v_mul_f32_e32 v1, 0x4f7ffffe, v1
	v_cvt_u32_f32_e32 v1, v1
	v_mul_lo_u32 v4, v4, v1
	v_mul_hi_u32 v4, v1, v4
	v_add_u32_e32 v1, v1, v4
	s_waitcnt vmcnt(0)
	v_mul_hi_u32 v1, v3, v1
	v_mul_lo_u32 v4, v1, v2
	v_sub_u32_e32 v4, v3, v4
	v_add_u32_e32 v5, 1, v1
	v_cmp_ge_u32_e32 vcc, v4, v2
	v_add_u32_e32 v3, 1, v3
	s_nop 0
	v_cndmask_b32_e32 v1, v1, v5, vcc
	v_sub_u32_e32 v5, v4, v2
	v_cndmask_b32_e32 v4, v4, v5, vcc
	v_add_u32_e32 v5, 1, v1
	v_cmp_ge_u32_e32 vcc, v4, v2
	s_nop 1
	v_cndmask_b32_e32 v1, v1, v5, vcc
	v_mul_lo_u32 v4, v2, v1
	v_add_u32_e32 v2, v4, v2
	v_cmp_ne_u32_e32 vcc, v3, v2
	s_and_saveexec_b64 s[4:5], vcc
	s_xor_b64 s[4:5], exec, s[4:5]
	s_cbranch_execz .LBB0_620
	s_waitcnt lgkmcnt(0)
	buffer_inv sc1
	s_waitcnt vmcnt(0)
	v_mov_b32_e32 v0, 0xc3000
	global_load_dword v0, v0, s[92:93] offset:1280 sc1
	s_add_u32 s10, s92, 0xc3500
	s_addc_u32 s11, s93, 0
	s_waitcnt vmcnt(0)
	v_cmp_eq_u32_e32 vcc, v0, v1
	s_and_saveexec_b64 s[6:7], vcc
	s_cbranch_execz .LBB0_619
	s_add_u32 s8, s92, 0xc0200
	s_addc_u32 s9, s93, 0
	s_mov_b32 s24, 1
	s_mov_b64 s[14:15], 0
	v_mov_b32_e32 v0, 0
	s_branch .LBB0_610

.LBB0_619:
	s_or_b64 exec, exec, s[6:7]
	s_waitcnt vmcnt(0)
	s_waitcnt vmcnt(0)
.LBB0_620:
	s_andn2_saveexec_b64 s[4:5], s[4:5]
	s_cbranch_execz .LBB0_638
	s_mov_b64 s[4:5], exec
	buffer_wbl2 sc1
	buffer_inv sc1
	s_waitcnt lgkmcnt(0)
	s_waitcnt vmcnt(0)
	v_mbcnt_lo_u32_b32 v1, s4, 0
	v_mbcnt_hi_u32_b32 v1, s5, v1
	v_cmp_eq_u32_e32 vcc, 0, v1
	s_and_saveexec_b64 s[6:7], vcc
	s_cbranch_execz .LBB0_623
	s_bcnt1_i32_b64 s4, s[4:5]
	v_mov_b32_e32 v2, 0xc3000
	v_mov_b32_e32 v3, s4
	global_atomic_add v2, v2, v3, s[92:93] offset:1024 sc0

.LBB0_637:
	s_or_b64 exec, exec, s[4:5]
	v_mov_b32_e32 v0, 0x2000
	v_mov_b32_e32 v1, 1
	s_waitcnt vmcnt(0)
	global_atomic_add v0, v1, s[2:3] offset:1024
	s_waitcnt vmcnt(0)

.LBB0_1114:
	v_readlane_b32 s4, v243, 5
	s_lshl_b32 s4, s4, 8
	v_readlane_b32 s6, v243, 3
	v_readlane_b32 s7, v243, 4
	s_add_u32 s4, s6, s4
	s_addc_u32 s5, s7, 0
	v_mov_b32_e32 v1, 0x1000
	v_mov_b32_e32 v3, 1
	global_atomic_add v3, v1, v3, s[4:5] offset:1024 sc0
	v_cvt_f32_u32_e32 v1, v2
	v_sub_u32_e32 v4, 0, v2
	v_rcp_iflag_f32_e32 v1, v1
	s_nop 0
	v_mul_f32_e32 v1, 0x4f7ffffe, v1
	v_cvt_u32_f32_e32 v1, v1
	v_mul_lo_u32 v4, v4, v1
	v_mul_hi_u32 v4, v1, v4
	v_add_u32_e32 v1, v1, v4
	s_waitcnt vmcnt(0)
	v_mul_hi_u32 v1, v3, v1
	v_mul_lo_u32 v4, v1, v2
	v_sub_u32_e32 v4, v3, v4
	v_add_u32_e32 v5, 1, v1
	v_cmp_ge_u32_e32 vcc, v4, v2
	v_add_u32_e32 v3, 1, v3
	s_nop 0
	v_cndmask_b32_e32 v1, v1, v5, vcc
	v_sub_u32_e32 v5, v4, v2
	v_cndmask_b32_e32 v4, v4, v5, vcc
	v_add_u32_e32 v5, 1, v1
	v_cmp_ge_u32_e32 vcc, v4, v2
	s_nop 1
	v_cndmask_b32_e32 v1, v1, v5, vcc
	v_mul_lo_u32 v4, v2, v1
	v_add_u32_e32 v2, v4, v2
	v_cmp_ne_u32_e32 vcc, v3, v2
	s_and_saveexec_b64 s[6:7], vcc
	s_xor_b64 s[6:7], exec, s[6:7]
	s_cbranch_execz .LBB0_1128
	s_waitcnt lgkmcnt(0)
	buffer_inv sc1
	s_waitcnt vmcnt(0)
	v_mov_b32_e32 v0, 0xc3000
	global_load_dword v0, v0, s[92:93] offset:1280 sc1
	s_add_u32 s18, s92, 0xc3500
	s_addc_u32 s19, s93, 0
	s_waitcnt vmcnt(0)
	v_cmp_eq_u32_e32 vcc, v0, v1
	s_and_saveexec_b64 s[8:9], vcc
	s_cbranch_execz .LBB0_1127
	s_add_u32 s12, s92, 0xc0200
	s_addc_u32 s13, s93, 0
	s_mov_b32 s14, 1
	s_mov_b64 s[20:21], 0
	v_mov_b32_e32 v0, 0
	s_branch .LBB0_1118

.LBB0_1350:
	v_readlane_b32 s4, v243, 5
	s_lshl_b32 s4, s4, 8
	v_readlane_b32 s6, v243, 3
	v_readlane_b32 s7, v243, 4
	s_add_u32 s4, s6, s4
	s_addc_u32 s5, s7, 0
	v_mov_b32_e32 v1, 0x1000
	v_mov_b32_e32 v3, 1
	global_atomic_add v3, v1, v3, s[4:5] offset:1024 sc0
	v_cvt_f32_u32_e32 v1, v2
	v_sub_u32_e32 v4, 0, v2
	v_rcp_iflag_f32_e32 v1, v1
	s_nop 0
	v_mul_f32_e32 v1, 0x4f7ffffe, v1
	v_cvt_u32_f32_e32 v1, v1
	v_mul_lo_u32 v4, v4, v1
	v_mul_hi_u32 v4, v1, v4
	v_add_u32_e32 v1, v1, v4
	s_waitcnt vmcnt(0)
	v_mul_hi_u32 v1, v3, v1
	v_mul_lo_u32 v4, v1, v2
	v_sub_u32_e32 v4, v3, v4
	v_add_u32_e32 v5, 1, v1
	v_cmp_ge_u32_e32 vcc, v4, v2
	v_add_u32_e32 v3, 1, v3
	s_nop 0
	v_cndmask_b32_e32 v1, v1, v5, vcc
	v_sub_u32_e32 v5, v4, v2
	v_cndmask_b32_e32 v4, v4, v5, vcc
	v_add_u32_e32 v5, 1, v1
	v_cmp_ge_u32_e32 vcc, v4, v2
	s_nop 1
	v_cndmask_b32_e32 v1, v1, v5, vcc
	v_mul_lo_u32 v4, v2, v1
	v_add_u32_e32 v2, v4, v2
	v_cmp_ne_u32_e32 vcc, v3, v2
	s_and_saveexec_b64 s[6:7], vcc
	s_xor_b64 s[6:7], exec, s[6:7]
	s_cbranch_execz .LBB0_1364
	s_waitcnt lgkmcnt(0)
	buffer_inv sc1
	s_waitcnt vmcnt(0)
	v_mov_b32_e32 v0, 0xc3000
	global_load_dword v0, v0, s[92:93] offset:1280 sc1
	s_add_u32 s12, s92, 0xc3500
	s_addc_u32 s13, s93, 0
	s_waitcnt vmcnt(0)
	v_cmp_eq_u32_e32 vcc, v0, v1
	s_and_saveexec_b64 s[8:9], vcc
	s_cbranch_execz .LBB0_1363
	s_add_u32 s10, s92, 0xc0200
	s_addc_u32 s11, s93, 0
	s_mov_b32 s24, 1
	s_mov_b64 s[14:15], 0
	v_mov_b32_e32 v0, 0
	s_branch .LBB0_1354

.LBB0_2069:
	v_readlane_b32 s2, v243, 5
	s_lshl_b32 s2, s2, 8
	v_readlane_b32 s4, v243, 3
	v_readlane_b32 s5, v243, 4
	s_add_u32 s2, s4, s2
	s_addc_u32 s3, s5, 0
	v_mov_b32_e32 v1, 0x1000
	v_mov_b32_e32 v3, 1
	global_atomic_add v3, v1, v3, s[2:3] offset:1024 sc0
	v_cvt_f32_u32_e32 v1, v2
	v_sub_u32_e32 v4, 0, v2
	v_rcp_iflag_f32_e32 v1, v1
	s_nop 0
	v_mul_f32_e32 v1, 0x4f7ffffe, v1
	v_cvt_u32_f32_e32 v1, v1
	v_mul_lo_u32 v4, v4, v1
	v_mul_hi_u32 v4, v1, v4
	v_add_u32_e32 v1, v1, v4
	s_waitcnt vmcnt(0)
	v_mul_hi_u32 v1, v3, v1
	v_mul_lo_u32 v4, v1, v2
	v_sub_u32_e32 v4, v3, v4
	v_add_u32_e32 v5, 1, v1
	v_cmp_ge_u32_e32 vcc, v4, v2
	v_add_u32_e32 v3, 1, v3
	s_nop 0
	v_cndmask_b32_e32 v1, v1, v5, vcc
	v_sub_u32_e32 v5, v4, v2
	v_cndmask_b32_e32 v4, v4, v5, vcc
	v_add_u32_e32 v5, 1, v1
	v_cmp_ge_u32_e32 vcc, v4, v2
	s_nop 1
	v_cndmask_b32_e32 v1, v1, v5, vcc
	v_mul_lo_u32 v4, v2, v1
	v_add_u32_e32 v2, v4, v2
	v_cmp_ne_u32_e32 vcc, v3, v2
	s_and_saveexec_b64 s[4:5], vcc
	s_xor_b64 s[4:5], exec, s[4:5]
	s_cbranch_execz .LBB0_2083
	s_waitcnt lgkmcnt(0)
	buffer_inv sc1
	s_waitcnt vmcnt(0)
	v_mov_b32_e32 v0, 0xc3000
	global_load_dword v0, v0, s[92:93] offset:1280 sc1
	s_add_u32 s10, s92, 0xc3500
	s_addc_u32 s11, s93, 0
	s_waitcnt vmcnt(0)
	v_cmp_eq_u32_e32 vcc, v0, v1
	s_and_saveexec_b64 s[6:7], vcc
	s_cbranch_execz .LBB0_2082
	s_add_u32 s8, s92, 0xc0200
	s_addc_u32 s9, s93, 0
	s_mov_b32 s22, 1
	s_mov_b64 s[12:13], 0
	v_mov_b32_e32 v0, 0
	s_branch .LBB0_2073
